# code placement: three 4-byte pads so that all five hand-written GEMM k-loop heads start at 0 mod 8 bytes
# baseline (speedup 1.0000x reference)
.LBB0_104:
	v_mov_b32_e32 v1, v168
	v_readlane_b32 s52, v254, 48
	v_readfirstlane_b32 s2, v1
	s_lshl_b32 s3, s2, 5
	s_lshl_b32 s2, s2, 6
	v_lshrrev_b32_e32 v3, 4, v1
	v_and_b32_e32 v4, 7, v1
	s_and_b32 s3, s3, 0xfffff000
	v_lshlrev_b32_e32 v1, 6, v1
	s_and_b32 s2, s2, 0x1000
	v_readlane_b32 s56, v254, 52
	v_bitop3_b32 v3, v3, v4, 3 bitop3:0x6c
	v_and_b32_e32 v1, 0x3c0, v1
	v_readlane_b32 s57, v254, 53
	s_add_u32 s36, s56, s21
	v_lshlrev_b32_e32 v69, 3, v3
	s_waitcnt vmcnt(0)
	v_or_b32_e32 v3, s3, v1
	v_or_b32_e32 v4, s2, v1
	s_addc_u32 s37, s57, s20
	s_lshl_b64 s[2:3], s[30:31], 1
	s_add_u32 s40, s56, s2
	s_waitcnt lgkmcnt(0)
	v_mov_b32_e32 v32, 0
	v_xor_b32_e32 v1, 32, v69
	s_addc_u32 s41, s57, s3
	s_mov_b64 s[42:43], 0
	s_mov_b32 s51, 0
	v_lshlrev_b32_e32 v3, 1, v3
	v_lshlrev_b32_e32 v68, 1, v4
	v_mov_b32_e32 v33, v32
	v_mov_b32_e32 v34, v32
	v_mov_b32_e32 v35, v32
	v_mov_b32_e32 v48, v32
	v_mov_b32_e32 v49, v32
	v_mov_b32_e32 v50, v32
	v_mov_b32_e32 v51, v32
	v_mov_b32_e32 v4, v32
	v_mov_b32_e32 v5, v32
	v_mov_b32_e32 v6, v32
	v_mov_b32_e32 v7, v32
	v_mov_b32_e32 v8, v32
	v_mov_b32_e32 v9, v32
	v_mov_b32_e32 v10, v32
	v_mov_b32_e32 v11, v32
	v_mov_b32_e32 v12, v32
	v_mov_b32_e32 v13, v32
	v_mov_b32_e32 v14, v32
	v_mov_b32_e32 v15, v32
	v_mov_b32_e32 v16, v32
	v_mov_b32_e32 v17, v32
	v_mov_b32_e32 v18, v32
	v_mov_b32_e32 v19, v32
	v_mov_b32_e32 v20, v32
	v_mov_b32_e32 v21, v32
	v_mov_b32_e32 v22, v32
	v_mov_b32_e32 v23, v32
	v_mov_b32_e32 v24, v32
	v_mov_b32_e32 v25, v32
	v_mov_b32_e32 v26, v32
	v_mov_b32_e32 v27, v32
	v_mov_b32_e32 v28, v32
	v_mov_b32_e32 v29, v32
	v_mov_b32_e32 v30, v32
	v_mov_b32_e32 v31, v32
	v_mov_b32_e32 v36, v32
	v_mov_b32_e32 v37, v32
	v_mov_b32_e32 v38, v32
	v_mov_b32_e32 v39, v32
	v_mov_b32_e32 v40, v32
	v_mov_b32_e32 v41, v32
	v_mov_b32_e32 v42, v32
	v_mov_b32_e32 v43, v32
	v_mov_b32_e32 v44, v32
	v_mov_b32_e32 v45, v32
	v_mov_b32_e32 v46, v32
	v_mov_b32_e32 v47, v32
	v_mov_b32_e32 v52, v32
	v_mov_b32_e32 v53, v32
	v_mov_b32_e32 v54, v32
	v_mov_b32_e32 v55, v32
	v_mov_b32_e32 v56, v32
	v_mov_b32_e32 v57, v32
	v_mov_b32_e32 v58, v32
	v_mov_b32_e32 v59, v32
	v_mov_b32_e32 v60, v32
	v_mov_b32_e32 v61, v32
	v_mov_b32_e32 v62, v32
	v_mov_b32_e32 v63, v32
	v_mov_b32_e32 v64, v32
	v_mov_b32_e32 v65, v32
	v_mov_b32_e32 v66, v32
	v_mov_b32_e32 v67, v32
	s_mov_b64 s[18:19], 0x1390080
	s_waitcnt vmcnt(0) lgkmcnt(0)
	s_barrier
	v_readlane_b32 s53, v254, 49
	v_readlane_b32 s54, v254, 50
	v_readlane_b32 s55, v254, 51
	v_readlane_b32 s58, v254, 54
	v_readlane_b32 s59, v254, 55
	v_lshlrev_b32_e32 v86, 1, v69
	v_add_u32_e32 v160, v3, v86
	v_add_u32_e32 v162, v68, v86
	v_lshlrev_b32_e32 v86, 1, v1
	v_add_u32_e32 v161, v3, v86
	v_add_u32_e32 v163, v68, v86
	v_lshrrev_b32_e32 v87, 3, v168
	v_xor_b32_e32 v86, v87, v168
	v_and_b32_e32 v86, 7, v86
	v_lshlrev_b32_e32 v86, 4, v86
	s_movk_i32 s35, 0x1600
	v_mad_u32_u24 v164, v87, s35, v86
	v_add_u32_e32 v165, 0x2c000, v164
	v_add_u32_e32 v166, 0x58000, v164
	v_add_u32_e32 v167, 0x84000, v164
	s_add_u32 s52, s36, 0x1390080
	s_addc_u32 s53, s37, 0
	s_add_u32 s54, s40, 0xf4b0080
	s_addc_u32 s55, s41, 0
	v_readfirstlane_b32 s35, v168
	s_lshl_b32 s35, s35, 4
	s_or_b32 s35, s35, 0x8000
	s_mov_b32 m0, s35
	s_nop 0
	global_load_lds_dwordx4 v164, s[52:53]
	s_add_u32 m0, s35, 0x1000
	s_nop 0
	global_load_lds_dwordx4 v165, s[52:53]
	s_add_u32 m0, s35, 0x2000
	s_nop 0
	global_load_lds_dwordx4 v166, s[52:53]
	s_add_u32 m0, s35, 0x3000
	s_nop 0
	global_load_lds_dwordx4 v167, s[52:53]
	s_add_u32 m0, s35, 0x4000
	s_nop 0
	global_load_lds_dwordx4 v164, s[54:55]
	s_add_u32 m0, s35, 0x5000
	s_nop 0
	global_load_lds_dwordx4 v165, s[54:55]
	s_add_u32 m0, s35, 0x6000
	s_nop 0
	global_load_lds_dwordx4 v166, s[54:55]
	s_add_u32 m0, s35, 0x7000
	s_nop 0
	global_load_lds_dwordx4 v167, s[54:55]
	s_add_u32 s52, s52, 0x80
	s_addc_u32 s53, s53, 0
	s_add_u32 s54, s54, 0x80
	s_addc_u32 s55, s55, 0
	s_xor_b32 s35, s35, 0x8000
	s_nop 0

.LBB0_121:
	v_mov_b32_e32 v1, v168
	v_readlane_b32 s60, v254, 48
	v_readfirstlane_b32 s2, v1
	s_lshl_b32 s3, s2, 5
	s_lshl_b32 s2, s2, 6
	s_and_b32 s3, s3, 0xfffff000
	s_and_b32 s2, s2, 0x1000
	v_readlane_b32 s64, v254, 52
	v_lshrrev_b32_e32 v3, 4, v1
	v_and_b32_e32 v4, 7, v1
	v_lshlrev_b32_e32 v1, 6, v1
	v_readlane_b32 s65, v254, 53
	s_add_u32 s50, s64, s50
	v_bitop3_b32 v3, v3, v4, 3 bitop3:0x6c
	s_waitcnt vmcnt(0)
	v_and_b32_e32 v1, 0x3c0, v1
	s_addc_u32 s51, s65, s51
	v_lshlrev_b32_e32 v69, 3, v3
	v_or_b32_e32 v3, s3, v1
	v_or_b32_e32 v4, s2, v1
	s_add_u32 s52, s64, s52
	s_waitcnt lgkmcnt(0)
	v_mov_b32_e32 v32, 0
	v_xor_b32_e32 v1, 32, v69
	s_addc_u32 s53, s65, s53
	s_mov_b64 s[54:55], 0
	s_mov_b32 s45, 0
	v_lshlrev_b32_e32 v3, 1, v3
	v_lshlrev_b32_e32 v68, 1, v4
	v_mov_b32_e32 v33, v32
	v_mov_b32_e32 v34, v32
	v_mov_b32_e32 v35, v32
	v_mov_b32_e32 v48, v32
	v_mov_b32_e32 v49, v32
	v_mov_b32_e32 v50, v32
	v_mov_b32_e32 v51, v32
	v_mov_b32_e32 v4, v32
	v_mov_b32_e32 v5, v32
	v_mov_b32_e32 v6, v32
	v_mov_b32_e32 v7, v32
	v_mov_b32_e32 v8, v32
	v_mov_b32_e32 v9, v32
	v_mov_b32_e32 v10, v32
	v_mov_b32_e32 v11, v32
	v_mov_b32_e32 v12, v32
	v_mov_b32_e32 v13, v32
	v_mov_b32_e32 v14, v32
	v_mov_b32_e32 v15, v32
	v_mov_b32_e32 v16, v32
	v_mov_b32_e32 v17, v32
	v_mov_b32_e32 v18, v32
	v_mov_b32_e32 v19, v32
	v_mov_b32_e32 v20, v32
	v_mov_b32_e32 v21, v32
	v_mov_b32_e32 v22, v32
	v_mov_b32_e32 v23, v32
	v_mov_b32_e32 v24, v32
	v_mov_b32_e32 v25, v32
	v_mov_b32_e32 v26, v32
	v_mov_b32_e32 v27, v32
	v_mov_b32_e32 v28, v32
	v_mov_b32_e32 v29, v32
	v_mov_b32_e32 v30, v32
	v_mov_b32_e32 v31, v32
	v_mov_b32_e32 v36, v32
	v_mov_b32_e32 v37, v32
	v_mov_b32_e32 v38, v32
	v_mov_b32_e32 v39, v32
	v_mov_b32_e32 v40, v32
	v_mov_b32_e32 v41, v32
	v_mov_b32_e32 v42, v32
	v_mov_b32_e32 v43, v32
	v_mov_b32_e32 v44, v32
	v_mov_b32_e32 v45, v32
	v_mov_b32_e32 v46, v32
	v_mov_b32_e32 v47, v32
	v_mov_b32_e32 v52, v32
	v_mov_b32_e32 v53, v32
	v_mov_b32_e32 v54, v32
	v_mov_b32_e32 v55, v32
	v_mov_b32_e32 v56, v32
	v_mov_b32_e32 v57, v32
	v_mov_b32_e32 v58, v32
	v_mov_b32_e32 v59, v32
	v_mov_b32_e32 v60, v32
	v_mov_b32_e32 v61, v32
	v_mov_b32_e32 v62, v32
	v_mov_b32_e32 v63, v32
	v_mov_b32_e32 v64, v32
	v_mov_b32_e32 v65, v32
	v_mov_b32_e32 v66, v32
	v_mov_b32_e32 v67, v32
	s_waitcnt vmcnt(0) lgkmcnt(0)
	s_barrier
	v_readlane_b32 s61, v254, 49
	v_readlane_b32 s62, v254, 50
	v_readlane_b32 s63, v254, 51
	v_readlane_b32 s66, v254, 54
	v_readlane_b32 s67, v254, 55
	v_lshlrev_b32_e32 v86, 1, v69
	v_add_u32_e32 v160, v3, v86
	v_add_u32_e32 v162, v68, v86
	v_lshlrev_b32_e32 v86, 1, v1
	v_add_u32_e32 v161, v3, v86
	v_add_u32_e32 v163, v68, v86
	v_lshrrev_b32_e32 v87, 3, v168
	v_xor_b32_e32 v86, v87, v168
	v_and_b32_e32 v86, 7, v86
	v_lshlrev_b32_e32 v86, 4, v86
	s_movk_i32 s60, 0x800
	v_mad_u32_u24 v164, v87, s60, v86
	v_add_u32_e32 v165, 0x10000, v164
	v_add_u32_e32 v166, 0x20000, v164
	v_add_u32_e32 v167, 0x30000, v164
	s_add_u32 s58, s50, s68
	s_addc_u32 s59, s51, s69
	s_add_u32 s34, s52, 0xa130080
	s_addc_u32 s35, s53, 0
	v_readfirstlane_b32 s60, v168
	s_lshl_b32 s60, s60, 4
	s_or_b32 s60, s60, 0x8000
	s_mov_b32 m0, s60
	s_nop 0
	global_load_lds_dwordx4 v164, s[58:59]
	s_add_u32 m0, s60, 0x1000
	s_nop 0
	global_load_lds_dwordx4 v165, s[58:59]
	s_add_u32 m0, s60, 0x2000
	s_nop 0
	global_load_lds_dwordx4 v166, s[58:59]
	s_add_u32 m0, s60, 0x3000
	s_nop 0
	global_load_lds_dwordx4 v167, s[58:59]
	s_add_u32 m0, s60, 0x4000
	s_nop 0
	global_load_lds_dwordx4 v164, s[34:35]
	s_add_u32 m0, s60, 0x5000
	s_nop 0
	global_load_lds_dwordx4 v165, s[34:35]
	s_add_u32 m0, s60, 0x6000
	s_nop 0
	global_load_lds_dwordx4 v166, s[34:35]
	s_add_u32 m0, s60, 0x7000
	s_nop 0
	global_load_lds_dwordx4 v167, s[34:35]
	s_add_u32 s58, s58, 0x80
	s_addc_u32 s59, s59, 0
	s_add_u32 s34, s34, 0x80
	s_addc_u32 s35, s35, 0
	s_xor_b32 s60, s60, 0x8000
	s_nop 0

.LBB0_148:
	v_mov_b32_e32 v1, v168
	v_readlane_b32 s52, v254, 48
	v_readfirstlane_b32 s2, v1
	v_lshrrev_b32_e32 v3, 4, v1
	v_and_b32_e32 v4, 7, v1
	s_lshl_b32 s3, s2, 5
	v_lshlrev_b32_e32 v1, 6, v1
	s_lshl_b32 s2, s2, 6
	v_bitop3_b32 v3, v3, v4, 3 bitop3:0x6c
	s_and_b32 s3, s3, 0xfffff000
	v_and_b32_e32 v1, 0x3c0, v1
	s_and_b32 s2, s2, 0x1000
	v_lshlrev_b32_e32 v69, 3, v3
	v_or_b32_e32 v3, s3, v1
	v_or_b32_e32 v4, s2, v1
	s_lshl_b64 s[2:3], s[38:39], 11
	v_readlane_b32 s56, v254, 52
	v_readlane_b32 s57, v254, 53
	s_add_u32 s40, s56, s2
	s_waitcnt vmcnt(0)
	s_addc_u32 s41, s57, s3
	s_lshl_b64 s[2:3], s[30:31], 1
	s_add_u32 s42, s56, s2
	s_waitcnt lgkmcnt(0)
	v_mov_b32_e32 v32, 0
	v_xor_b32_e32 v1, 32, v69
	s_addc_u32 s43, s57, s3
	s_mov_b64 s[44:45], 0
	s_mov_b32 s51, 0
	v_lshlrev_b32_e32 v3, 1, v3
	v_lshlrev_b32_e32 v68, 1, v4
	v_mov_b32_e32 v33, v32
	v_mov_b32_e32 v34, v32
	v_mov_b32_e32 v35, v32
	v_mov_b32_e32 v48, v32
	v_mov_b32_e32 v49, v32
	v_mov_b32_e32 v50, v32
	v_mov_b32_e32 v51, v32
	v_mov_b32_e32 v4, v32
	v_mov_b32_e32 v5, v32
	v_mov_b32_e32 v6, v32
	v_mov_b32_e32 v7, v32
	v_mov_b32_e32 v8, v32
	v_mov_b32_e32 v9, v32
	v_mov_b32_e32 v10, v32
	v_mov_b32_e32 v11, v32
	v_mov_b32_e32 v12, v32
	v_mov_b32_e32 v13, v32
	v_mov_b32_e32 v14, v32
	v_mov_b32_e32 v15, v32
	v_mov_b32_e32 v16, v32
	v_mov_b32_e32 v17, v32
	v_mov_b32_e32 v18, v32
	v_mov_b32_e32 v19, v32
	v_mov_b32_e32 v20, v32
	v_mov_b32_e32 v21, v32
	v_mov_b32_e32 v22, v32
	v_mov_b32_e32 v23, v32
	v_mov_b32_e32 v24, v32
	v_mov_b32_e32 v25, v32
	v_mov_b32_e32 v26, v32
	v_mov_b32_e32 v27, v32
	v_mov_b32_e32 v28, v32
	v_mov_b32_e32 v29, v32
	v_mov_b32_e32 v30, v32
	v_mov_b32_e32 v31, v32
	v_mov_b32_e32 v36, v32
	v_mov_b32_e32 v37, v32
	v_mov_b32_e32 v38, v32
	v_mov_b32_e32 v39, v32
	v_mov_b32_e32 v40, v32
	v_mov_b32_e32 v41, v32
	v_mov_b32_e32 v42, v32
	v_mov_b32_e32 v43, v32
	v_mov_b32_e32 v44, v32
	v_mov_b32_e32 v45, v32
	v_mov_b32_e32 v46, v32
	v_mov_b32_e32 v47, v32
	v_mov_b32_e32 v52, v32
	v_mov_b32_e32 v53, v32
	v_mov_b32_e32 v54, v32
	v_mov_b32_e32 v55, v32
	v_mov_b32_e32 v56, v32
	v_mov_b32_e32 v57, v32
	v_mov_b32_e32 v58, v32
	v_mov_b32_e32 v59, v32
	v_mov_b32_e32 v60, v32
	v_mov_b32_e32 v61, v32
	v_mov_b32_e32 v62, v32
	v_mov_b32_e32 v63, v32
	v_mov_b32_e32 v64, v32
	v_mov_b32_e32 v65, v32
	v_mov_b32_e32 v66, v32
	v_mov_b32_e32 v67, v32
	s_mov_b64 s[18:19], 0x1390080
	s_waitcnt vmcnt(0) lgkmcnt(0)
	s_barrier
	v_readlane_b32 s53, v254, 49
	v_readlane_b32 s54, v254, 50
	v_readlane_b32 s55, v254, 51
	v_readlane_b32 s58, v254, 54
	v_readlane_b32 s59, v254, 55
	v_lshlrev_b32_e32 v86, 1, v69
	v_add_u32_e32 v160, v3, v86
	v_add_u32_e32 v162, v68, v86
	v_lshlrev_b32_e32 v86, 1, v1
	v_add_u32_e32 v161, v3, v86
	v_add_u32_e32 v163, v68, v86
	v_lshrrev_b32_e32 v87, 3, v168
	v_xor_b32_e32 v86, v87, v168
	v_and_b32_e32 v86, 7, v86
	v_lshlrev_b32_e32 v86, 4, v86
	s_movk_i32 s35, 0x800
	v_mad_u32_u24 v164, v87, s35, v86
	v_add_u32_e32 v165, 0x10000, v164
	v_add_u32_e32 v166, 0x20000, v164
	v_add_u32_e32 v167, 0x30000, v164
	s_add_u32 s52, s40, 0x1390080
	s_addc_u32 s53, s41, 0
	s_add_u32 s54, s42, 0x1190080
	s_addc_u32 s55, s43, 0
	v_readfirstlane_b32 s35, v168
	s_lshl_b32 s35, s35, 4
	s_or_b32 s35, s35, 0x8000
	s_mov_b32 m0, s35
	s_nop 0
	global_load_lds_dwordx4 v164, s[52:53]
	s_add_u32 m0, s35, 0x1000
	s_nop 0
	global_load_lds_dwordx4 v165, s[52:53]
	s_add_u32 m0, s35, 0x2000
	s_nop 0
	global_load_lds_dwordx4 v166, s[52:53]
	s_add_u32 m0, s35, 0x3000
	s_nop 0
	global_load_lds_dwordx4 v167, s[52:53]
	s_add_u32 m0, s35, 0x4000
	s_nop 0
	global_load_lds_dwordx4 v164, s[54:55]
	s_add_u32 m0, s35, 0x5000
	s_nop 0
	global_load_lds_dwordx4 v165, s[54:55]
	s_add_u32 m0, s35, 0x6000
	s_nop 0
	global_load_lds_dwordx4 v166, s[54:55]
	s_add_u32 m0, s35, 0x7000
	s_nop 0
	global_load_lds_dwordx4 v167, s[54:55]
	s_add_u32 s52, s52, 0x80
	s_addc_u32 s53, s53, 0
	s_add_u32 s54, s54, 0x80
	s_addc_u32 s55, s55, 0
	s_xor_b32 s35, s35, 0x8000
	s_nop 0
